# SwiGLU epilogue rewritten: row scale folded into exponent constant and rs^2, packed ops, no hazard nops
# baseline (speedup 1.0000x reference)
; #define LAS __attribute__((address_space(3)))
; __device__ __forceinline__ unsigned cvt_pk_bf16(float lo, float hi) { f32x2_t v = {lo, hi}; bf16x2_t b = __builtin_convertvector(v, bf16x2_t); return __builtin_bit_cast(unsigned, b); }
; __device__ __forceinline__ float sigm(float x) { return __builtin_amdgcn_rcpf(1.0f + __expf(-x)); }
; __device__ __forceinline__ int opaque_tid() { int t = threadIdx.x; asm volatile("" : "+v"(t)); return t; }
;     __device__ __forceinline__ void operator()(AccRef acc, const pg8::Unit& u, int, int, int, int) const {
;         const int tid = opaque_tid(), wid = __builtin_amdgcn_readfirstlane(tid >> 6), wr = wid >> 2, wc = wid & 3, fr = tid & 15, fq = (tid & 63) >> 4;
;         const int row0 = u.pm * 256 + wr * 64 + fr, col0 = u.pn * 128 + wc * 32 + 8 * fq;
; #pragma unroll
;         for (int ai = 0; ai < 2; ++ai)
; #pragma unroll
;             for (int m = 0; m < 4; ++m) {
;                 const int row = row0 + ai * 128 + m * 16; const float rs = ((const LAS float*)((LAS unsigned char*)g_lds + pg8::RSL_OFF))[wid * 128 + ai * 64 + m * 16 + fr];
;                 float o[8];
; #pragma unroll
;                 for (int n = 0; n < 2; ++n)
; #pragma unroll
;                     for (int j = 0; j < 4; ++j) { const float gv = acc[ai][0][m][n][j] * rs, uv = acc[ai][1][m][n][j] * rs; o[n * 4 + j] = gv * sigm(gv) * uv; }
;                 v4u w; w.x = cvt_pk_bf16(o[0], o[1]); w.y = cvt_pk_bf16(o[2], o[3]); w.z = cvt_pk_bf16(o[4], o[5]); w.w = cvt_pk_bf16(o[6], o[7]);
;                 *(v4u*)(O + (size_t)row * DFFP + col0) = w; }
.LBB0_309:
	v_mov_b32_e32 v140, v155
	s_lshl_b32 s11, s34, 7
	v_readfirstlane_b32 s6, v140
	v_and_b32_e32 v141, 15, v140
	s_ashr_i32 s7, s6, 6
	v_or_b32_e32 v142, s1, v141
	s_lshl_b32 s1, s7, 9
	s_ashr_i32 s6, s6, 2
	v_lshl_add_u32 v141, v141, 2, s1
	s_andn2_b32 s6, s6, 63
	v_add_u32_e32 v149, 0x20000, v141
	v_add_u32_e32 v148, s6, v142
	ds_read2_b32 v[240:241], v149 offset1:16
	ds_read2_b32 v[242:243], v149 offset0:32 offset1:48
	ds_read2_b32 v[244:245], v149 offset0:64 offset1:80
	ds_read2_b32 v[246:247], v149 offset0:96 offset1:112
	s_lshl_b32 s18, s7, 5
	v_readlane_b32 s6, v254, 43
	s_and_b32 s18, s18, 0x60
	v_readlane_b32 s7, v254, 44
	s_or_b32 s11, s18, s11
	v_lshrrev_b32_e32 v140, 1, v140
	s_movk_i32 s1, 0x1600
	v_and_or_b32 v140, v140, 24, s11
	v_mov_b32_e32 v150, 1.0
	v_ashrrev_i32_e32 v141, 31, v140
	v_mov_b64_e32 v[142:143], s[6:7]
	v_lshlrev_b64 v[140:141], 1, v[140:141]
	v_mad_i64_i32 v[252:253], s[6:7], v148, s1, v[142:143]
	v_lshl_add_u64 v[252:253], v[252:253], 0, v[140:141]
	s_waitcnt lgkmcnt(0)
	v_mul_f32_e32 v248, 0xbfb8aa3b, v240
	v_mul_f32_e32 v250, v240, v240
	v_pk_mul_f32 v[122:123], v[122:123], v[126:127]
	v_pk_mul_f32 v[124:125], v[124:125], v[128:129]
	v_pk_mul_f32 v[114:115], v[114:115], v[118:119]
	v_pk_mul_f32 v[116:117], v[116:117], v[120:121]
	v_pk_mul_f32 v[126:127], v[126:127], v[248:249] op_sel_hi:[1,0]
	v_pk_mul_f32 v[128:129], v[128:129], v[248:249] op_sel_hi:[1,0]
	v_pk_mul_f32 v[118:119], v[118:119], v[248:249] op_sel_hi:[1,0]
	v_pk_mul_f32 v[120:121], v[120:121], v[248:249] op_sel_hi:[1,0]
	v_exp_f32_e32 v126, v126
	v_exp_f32_e32 v127, v127
	v_exp_f32_e32 v128, v128
	v_exp_f32_e32 v129, v129
	v_exp_f32_e32 v118, v118
	v_exp_f32_e32 v119, v119
	v_exp_f32_e32 v120, v120
	v_exp_f32_e32 v121, v121
	v_pk_mul_f32 v[122:123], v[122:123], v[250:251] op_sel_hi:[1,0]
	v_pk_mul_f32 v[124:125], v[124:125], v[250:251] op_sel_hi:[1,0]
	v_pk_mul_f32 v[114:115], v[114:115], v[250:251] op_sel_hi:[1,0]
	v_pk_mul_f32 v[116:117], v[116:117], v[250:251] op_sel_hi:[1,0]
	v_pk_add_f32 v[126:127], v[126:127], v[150:151] op_sel_hi:[1,0]
	v_pk_add_f32 v[128:129], v[128:129], v[150:151] op_sel_hi:[1,0]
	v_pk_add_f32 v[118:119], v[118:119], v[150:151] op_sel_hi:[1,0]
	v_pk_add_f32 v[120:121], v[120:121], v[150:151] op_sel_hi:[1,0]
	v_rcp_f32_e32 v126, v126
	v_rcp_f32_e32 v127, v127
	v_rcp_f32_e32 v128, v128
	v_rcp_f32_e32 v129, v129
	v_rcp_f32_e32 v118, v118
	v_rcp_f32_e32 v119, v119
	v_rcp_f32_e32 v120, v120
	v_rcp_f32_e32 v121, v121
	v_pk_mul_f32 v[122:123], v[122:123], v[126:127]
	v_pk_mul_f32 v[124:125], v[124:125], v[128:129]
	v_pk_mul_f32 v[114:115], v[114:115], v[118:119]
	v_pk_mul_f32 v[116:117], v[116:117], v[120:121]
	v_cvt_pk_bf16_f32 v232, v122, v123
	v_cvt_pk_bf16_f32 v233, v124, v125
	v_cvt_pk_bf16_f32 v234, v114, v115
	v_cvt_pk_bf16_f32 v235, v116, v117
	global_store_dwordx4 v[252:253], v[232:235], off
	v_add_co_u32_e32 v252, vcc, 0x16000, v252
	s_nop 1
	v_addc_co_u32_e32 v253, vcc, 0, v253, vcc
	v_mul_f32_e32 v248, 0xbfb8aa3b, v241
	v_mul_f32_e32 v250, v241, v241
	v_pk_mul_f32 v[106:107], v[106:107], v[110:111]
	v_pk_mul_f32 v[108:109], v[108:109], v[112:113]
	v_pk_mul_f32 v[98:99], v[98:99], v[102:103]
	v_pk_mul_f32 v[100:101], v[100:101], v[104:105]
	v_pk_mul_f32 v[110:111], v[110:111], v[248:249] op_sel_hi:[1,0]
	v_pk_mul_f32 v[112:113], v[112:113], v[248:249] op_sel_hi:[1,0]
	v_pk_mul_f32 v[102:103], v[102:103], v[248:249] op_sel_hi:[1,0]
	v_pk_mul_f32 v[104:105], v[104:105], v[248:249] op_sel_hi:[1,0]
	v_exp_f32_e32 v110, v110
	v_exp_f32_e32 v111, v111
	v_exp_f32_e32 v112, v112
	v_exp_f32_e32 v113, v113
	v_exp_f32_e32 v102, v102
	v_exp_f32_e32 v103, v103
	v_exp_f32_e32 v104, v104
	v_exp_f32_e32 v105, v105
	v_pk_mul_f32 v[106:107], v[106:107], v[250:251] op_sel_hi:[1,0]
	v_pk_mul_f32 v[108:109], v[108:109], v[250:251] op_sel_hi:[1,0]
	v_pk_mul_f32 v[98:99], v[98:99], v[250:251] op_sel_hi:[1,0]
	v_pk_mul_f32 v[100:101], v[100:101], v[250:251] op_sel_hi:[1,0]
	v_pk_add_f32 v[110:111], v[110:111], v[150:151] op_sel_hi:[1,0]
	v_pk_add_f32 v[112:113], v[112:113], v[150:151] op_sel_hi:[1,0]
	v_pk_add_f32 v[102:103], v[102:103], v[150:151] op_sel_hi:[1,0]
	v_pk_add_f32 v[104:105], v[104:105], v[150:151] op_sel_hi:[1,0]
	v_rcp_f32_e32 v110, v110
	v_rcp_f32_e32 v111, v111
	v_rcp_f32_e32 v112, v112
	v_rcp_f32_e32 v113, v113
	v_rcp_f32_e32 v102, v102
	v_rcp_f32_e32 v103, v103
	v_rcp_f32_e32 v104, v104
	v_rcp_f32_e32 v105, v105
	v_pk_mul_f32 v[106:107], v[106:107], v[110:111]
	v_pk_mul_f32 v[108:109], v[108:109], v[112:113]
	v_pk_mul_f32 v[98:99], v[98:99], v[102:103]
	v_pk_mul_f32 v[100:101], v[100:101], v[104:105]
	v_cvt_pk_bf16_f32 v236, v106, v107
	v_cvt_pk_bf16_f32 v237, v108, v109
	v_cvt_pk_bf16_f32 v238, v98, v99
	v_cvt_pk_bf16_f32 v239, v100, v101
	global_store_dwordx4 v[252:253], v[236:239], off
	v_add_co_u32_e32 v252, vcc, 0x16000, v252
	s_nop 1
	v_addc_co_u32_e32 v253, vcc, 0, v253, vcc
	v_mul_f32_e32 v248, 0xbfb8aa3b, v242
	v_mul_f32_e32 v250, v242, v242
	v_pk_mul_f32 v[90:91], v[90:91], v[94:95]
	v_pk_mul_f32 v[92:93], v[92:93], v[96:97]
	v_pk_mul_f32 v[82:83], v[82:83], v[86:87]
	v_pk_mul_f32 v[84:85], v[84:85], v[88:89]
	v_pk_mul_f32 v[94:95], v[94:95], v[248:249] op_sel_hi:[1,0]
	v_pk_mul_f32 v[96:97], v[96:97], v[248:249] op_sel_hi:[1,0]
	v_pk_mul_f32 v[86:87], v[86:87], v[248:249] op_sel_hi:[1,0]
	v_pk_mul_f32 v[88:89], v[88:89], v[248:249] op_sel_hi:[1,0]
	v_exp_f32_e32 v94, v94
	v_exp_f32_e32 v95, v95
	v_exp_f32_e32 v96, v96
	v_exp_f32_e32 v97, v97
	v_exp_f32_e32 v86, v86
	v_exp_f32_e32 v87, v87
	v_exp_f32_e32 v88, v88
	v_exp_f32_e32 v89, v89
	v_pk_mul_f32 v[90:91], v[90:91], v[250:251] op_sel_hi:[1,0]
; #define LAS __attribute__((address_space(3)))
; __device__ __forceinline__ unsigned cvt_pk_bf16(float lo, float hi) { f32x2_t v = {lo, hi}; bf16x2_t b = __builtin_convertvector(v, bf16x2_t); return __builtin_bit_cast(unsigned, b); }
; __device__ __forceinline__ float sigm(float x) { return __builtin_amdgcn_rcpf(1.0f + __expf(-x)); }
;     __device__ __forceinline__ void operator()(AccRef acc, const pg8::Unit& u, int, int, int, int) const {
;     ...
;                 const int row = row0 + ai * 128 + m * 16; const float rs = ((const LAS float*)((LAS unsigned char*)g_lds + pg8::RSL_OFF))[wid * 128 + ai * 64 + m * 16 + fr];
;                 float o[8];
; #pragma unroll
;                 for (int n = 0; n < 2; ++n)
; #pragma unroll
;                     for (int j = 0; j < 4; ++j) { const float gv = acc[ai][0][m][n][j] * rs, uv = acc[ai][1][m][n][j] * rs; o[n * 4 + j] = gv * sigm(gv) * uv; }
;                 v4u w; w.x = cvt_pk_bf16(o[0], o[1]); w.y = cvt_pk_bf16(o[2], o[3]); w.z = cvt_pk_bf16(o[4], o[5]); w.w = cvt_pk_bf16(o[6], o[7]);
;                 *(v4u*)(O + (size_t)row * DFFP + col0) = w; }
	v_pk_mul_f32 v[92:93], v[92:93], v[250:251] op_sel_hi:[1,0]
	v_pk_mul_f32 v[82:83], v[82:83], v[250:251] op_sel_hi:[1,0]
	v_pk_mul_f32 v[84:85], v[84:85], v[250:251] op_sel_hi:[1,0]
	v_pk_add_f32 v[94:95], v[94:95], v[150:151] op_sel_hi:[1,0]
	v_pk_add_f32 v[96:97], v[96:97], v[150:151] op_sel_hi:[1,0]
	v_pk_add_f32 v[86:87], v[86:87], v[150:151] op_sel_hi:[1,0]
	v_pk_add_f32 v[88:89], v[88:89], v[150:151] op_sel_hi:[1,0]
	v_rcp_f32_e32 v94, v94
	v_rcp_f32_e32 v95, v95
	v_rcp_f32_e32 v96, v96
	v_rcp_f32_e32 v97, v97
	v_rcp_f32_e32 v86, v86
	v_rcp_f32_e32 v87, v87
	v_rcp_f32_e32 v88, v88
	v_rcp_f32_e32 v89, v89
	v_pk_mul_f32 v[90:91], v[90:91], v[94:95]
	v_pk_mul_f32 v[92:93], v[92:93], v[96:97]
	v_pk_mul_f32 v[82:83], v[82:83], v[86:87]
	v_pk_mul_f32 v[84:85], v[84:85], v[88:89]
	v_cvt_pk_bf16_f32 v232, v90, v91
	v_cvt_pk_bf16_f32 v233, v92, v93
	v_cvt_pk_bf16_f32 v234, v82, v83
	v_cvt_pk_bf16_f32 v235, v84, v85
	global_store_dwordx4 v[252:253], v[232:235], off
	v_add_co_u32_e32 v252, vcc, 0x16000, v252
	s_nop 1
	v_addc_co_u32_e32 v253, vcc, 0, v253, vcc
	v_mul_f32_e32 v248, 0xbfb8aa3b, v243
	v_mul_f32_e32 v250, v243, v243
	v_pk_mul_f32 v[74:75], v[74:75], v[78:79]
	v_pk_mul_f32 v[76:77], v[76:77], v[80:81]
	v_pk_mul_f32 v[66:67], v[66:67], v[70:71]
	v_pk_mul_f32 v[68:69], v[68:69], v[72:73]
	v_pk_mul_f32 v[78:79], v[78:79], v[248:249] op_sel_hi:[1,0]
	v_pk_mul_f32 v[80:81], v[80:81], v[248:249] op_sel_hi:[1,0]
	v_pk_mul_f32 v[70:71], v[70:71], v[248:249] op_sel_hi:[1,0]
	v_pk_mul_f32 v[72:73], v[72:73], v[248:249] op_sel_hi:[1,0]
	v_exp_f32_e32 v78, v78
	v_exp_f32_e32 v79, v79
	v_exp_f32_e32 v80, v80
	v_exp_f32_e32 v81, v81
	v_exp_f32_e32 v70, v70
	v_exp_f32_e32 v71, v71
	v_exp_f32_e32 v72, v72
	v_exp_f32_e32 v73, v73
	v_pk_mul_f32 v[74:75], v[74:75], v[250:251] op_sel_hi:[1,0]
	v_pk_mul_f32 v[76:77], v[76:77], v[250:251] op_sel_hi:[1,0]
	v_pk_mul_f32 v[66:67], v[66:67], v[250:251] op_sel_hi:[1,0]
	v_pk_mul_f32 v[68:69], v[68:69], v[250:251] op_sel_hi:[1,0]
	v_pk_add_f32 v[78:79], v[78:79], v[150:151] op_sel_hi:[1,0]
	v_pk_add_f32 v[80:81], v[80:81], v[150:151] op_sel_hi:[1,0]
	v_pk_add_f32 v[70:71], v[70:71], v[150:151] op_sel_hi:[1,0]
	v_pk_add_f32 v[72:73], v[72:73], v[150:151] op_sel_hi:[1,0]
	v_rcp_f32_e32 v78, v78
	v_rcp_f32_e32 v79, v79
	v_rcp_f32_e32 v80, v80
	v_rcp_f32_e32 v81, v81
	v_rcp_f32_e32 v70, v70
	v_rcp_f32_e32 v71, v71
	v_rcp_f32_e32 v72, v72
	v_rcp_f32_e32 v73, v73
	v_pk_mul_f32 v[74:75], v[74:75], v[78:79]
	v_pk_mul_f32 v[76:77], v[76:77], v[80:81]
	v_pk_mul_f32 v[66:67], v[66:67], v[70:71]
	v_pk_mul_f32 v[68:69], v[68:69], v[72:73]
	v_cvt_pk_bf16_f32 v236, v74, v75
	v_cvt_pk_bf16_f32 v237, v76, v77
	v_cvt_pk_bf16_f32 v238, v66, v67
	v_cvt_pk_bf16_f32 v239, v68, v69
	global_store_dwordx4 v[252:253], v[236:239], off
	v_add_co_u32_e32 v252, vcc, 0x6e000, v252
	s_nop 1
	v_addc_co_u32_e32 v253, vcc, 0, v253, vcc
	v_mul_f32_e32 v248, 0xbfb8aa3b, v244
	v_mul_f32_e32 v250, v244, v244
	v_pk_mul_f32 v[58:59], v[58:59], v[62:63]
	v_pk_mul_f32 v[60:61], v[60:61], v[64:65]
	v_pk_mul_f32 v[50:51], v[50:51], v[54:55]
	v_pk_mul_f32 v[52:53], v[52:53], v[56:57]
	v_pk_mul_f32 v[62:63], v[62:63], v[248:249] op_sel_hi:[1,0]
	v_pk_mul_f32 v[64:65], v[64:65], v[248:249] op_sel_hi:[1,0]
	v_pk_mul_f32 v[54:55], v[54:55], v[248:249] op_sel_hi:[1,0]
	v_pk_mul_f32 v[56:57], v[56:57], v[248:249] op_sel_hi:[1,0]
	v_exp_f32_e32 v62, v62
	v_exp_f32_e32 v63, v63
	v_exp_f32_e32 v64, v64
	v_exp_f32_e32 v65, v65
	v_exp_f32_e32 v54, v54
	v_exp_f32_e32 v55, v55
	v_exp_f32_e32 v56, v56
	v_exp_f32_e32 v57, v57
	v_pk_mul_f32 v[58:59], v[58:59], v[250:251] op_sel_hi:[1,0]
	v_pk_mul_f32 v[60:61], v[60:61], v[250:251] op_sel_hi:[1,0]
	v_pk_mul_f32 v[50:51], v[50:51], v[250:251] op_sel_hi:[1,0]
	v_pk_mul_f32 v[52:53], v[52:53], v[250:251] op_sel_hi:[1,0]
	v_pk_add_f32 v[62:63], v[62:63], v[150:151] op_sel_hi:[1,0]
	v_pk_add_f32 v[64:65], v[64:65], v[150:151] op_sel_hi:[1,0]
	v_pk_add_f32 v[54:55], v[54:55], v[150:151] op_sel_hi:[1,0]
	v_pk_add_f32 v[56:57], v[56:57], v[150:151] op_sel_hi:[1,0]
	v_rcp_f32_e32 v62, v62
	v_rcp_f32_e32 v63, v63
	v_rcp_f32_e32 v64, v64
	v_rcp_f32_e32 v65, v65
	v_rcp_f32_e32 v54, v54
	v_rcp_f32_e32 v55, v55
	v_rcp_f32_e32 v56, v56
	v_rcp_f32_e32 v57, v57
	v_pk_mul_f32 v[58:59], v[58:59], v[62:63]
	v_pk_mul_f32 v[60:61], v[60:61], v[64:65]
	v_pk_mul_f32 v[50:51], v[50:51], v[54:55]
	v_pk_mul_f32 v[52:53], v[52:53], v[56:57]
	v_cvt_pk_bf16_f32 v232, v58, v59
	v_cvt_pk_bf16_f32 v233, v60, v61
	v_cvt_pk_bf16_f32 v234, v50, v51
	v_cvt_pk_bf16_f32 v235, v52, v53
	global_store_dwordx4 v[252:253], v[232:235], off
	v_add_co_u32_e32 v252, vcc, 0x16000, v252
	s_nop 1
	v_addc_co_u32_e32 v253, vcc, 0, v253, vcc
	v_mul_f32_e32 v248, 0xbfb8aa3b, v245
	v_mul_f32_e32 v250, v245, v245
	v_pk_mul_f32 v[42:43], v[42:43], v[46:47]
	v_pk_mul_f32 v[44:45], v[44:45], v[48:49]
	v_pk_mul_f32 v[34:35], v[34:35], v[38:39]
	v_pk_mul_f32 v[36:37], v[36:37], v[40:41]
	v_pk_mul_f32 v[46:47], v[46:47], v[248:249] op_sel_hi:[1,0]
	v_pk_mul_f32 v[48:49], v[48:49], v[248:249] op_sel_hi:[1,0]
; #define LAS __attribute__((address_space(3)))
; __device__ __forceinline__ unsigned cvt_pk_bf16(float lo, float hi) { f32x2_t v = {lo, hi}; bf16x2_t b = __builtin_convertvector(v, bf16x2_t); return __builtin_bit_cast(unsigned, b); }
; __device__ __forceinline__ float sigm(float x) { return __builtin_amdgcn_rcpf(1.0f + __expf(-x)); }
; #define PG8_BAR __builtin_amdgcn_s_barrier()
; template <class Epi, bool ALIGN_EPI>
; __device__ __forceinline__ void gemm_phase(LAS unsigned char* lds, const Gemm g, const StaticOrder& S, const Epi& E) {
;     ...
;         if (!has_next) break;
; #pragma unroll
;         for (int a = 0; a < 2; ++a)
; #pragma unroll
;             for (int b = 0; b < 2; ++b)
; #pragma unroll
;                 for (int m = 0; m < 4; ++m)
; #pragma unroll
;                     for (int n = 0; n < 2; ++n) acc[a][b][m][n] = (f32x4){0.f, 0.f, 0.f, 0.f};
;         cur = nxt; cA = nA; cB = nB; ++ui;
;         if constexpr (ALIGN_EPI) { if (wr == 1) PG8_BAR; }
;     __device__ __forceinline__ void operator()(AccRef acc, const pg8::Unit& u, int, int, int, int) const {
;     ...
;                 const int row = row0 + ai * 128 + m * 16; const float rs = ((const LAS float*)((LAS unsigned char*)g_lds + pg8::RSL_OFF))[wid * 128 + ai * 64 + m * 16 + fr];
;                 float o[8];
; #pragma unroll
;                 for (int n = 0; n < 2; ++n)
; #pragma unroll
;                     for (int j = 0; j < 4; ++j) { const float gv = acc[ai][0][m][n][j] * rs, uv = acc[ai][1][m][n][j] * rs; o[n * 4 + j] = gv * sigm(gv) * uv; }
;                 v4u w; w.x = cvt_pk_bf16(o[0], o[1]); w.y = cvt_pk_bf16(o[2], o[3]); w.z = cvt_pk_bf16(o[4], o[5]); w.w = cvt_pk_bf16(o[6], o[7]);
;                 *(v4u*)(O + (size_t)row * DFFP + col0) = w; }
	v_pk_mul_f32 v[38:39], v[38:39], v[248:249] op_sel_hi:[1,0]
	v_pk_mul_f32 v[40:41], v[40:41], v[248:249] op_sel_hi:[1,0]
	v_exp_f32_e32 v46, v46
	v_exp_f32_e32 v47, v47
	v_exp_f32_e32 v48, v48
	v_exp_f32_e32 v49, v49
	v_exp_f32_e32 v38, v38
	v_exp_f32_e32 v39, v39
	v_exp_f32_e32 v40, v40
	v_exp_f32_e32 v41, v41
	v_pk_mul_f32 v[42:43], v[42:43], v[250:251] op_sel_hi:[1,0]
	v_pk_mul_f32 v[44:45], v[44:45], v[250:251] op_sel_hi:[1,0]
	v_pk_mul_f32 v[34:35], v[34:35], v[250:251] op_sel_hi:[1,0]
	v_pk_mul_f32 v[36:37], v[36:37], v[250:251] op_sel_hi:[1,0]
	v_pk_add_f32 v[46:47], v[46:47], v[150:151] op_sel_hi:[1,0]
	v_pk_add_f32 v[48:49], v[48:49], v[150:151] op_sel_hi:[1,0]
	v_pk_add_f32 v[38:39], v[38:39], v[150:151] op_sel_hi:[1,0]
	v_pk_add_f32 v[40:41], v[40:41], v[150:151] op_sel_hi:[1,0]
	v_rcp_f32_e32 v46, v46
	v_rcp_f32_e32 v47, v47
	v_rcp_f32_e32 v48, v48
	v_rcp_f32_e32 v49, v49
	v_rcp_f32_e32 v38, v38
	v_rcp_f32_e32 v39, v39
	v_rcp_f32_e32 v40, v40
	v_rcp_f32_e32 v41, v41
	v_pk_mul_f32 v[42:43], v[42:43], v[46:47]
	v_pk_mul_f32 v[44:45], v[44:45], v[48:49]
	v_pk_mul_f32 v[34:35], v[34:35], v[38:39]
	v_pk_mul_f32 v[36:37], v[36:37], v[40:41]
	v_cvt_pk_bf16_f32 v236, v42, v43
	v_cvt_pk_bf16_f32 v237, v44, v45
	v_cvt_pk_bf16_f32 v238, v34, v35
	v_cvt_pk_bf16_f32 v239, v36, v37
	global_store_dwordx4 v[252:253], v[236:239], off
	v_add_co_u32_e32 v252, vcc, 0x16000, v252
	s_nop 1
	v_addc_co_u32_e32 v253, vcc, 0, v253, vcc
	v_mul_f32_e32 v248, 0xbfb8aa3b, v246
	v_mul_f32_e32 v250, v246, v246
	v_pk_mul_f32 v[26:27], v[26:27], v[30:31]
	v_pk_mul_f32 v[28:29], v[28:29], v[32:33]
	v_pk_mul_f32 v[18:19], v[18:19], v[22:23]
	v_pk_mul_f32 v[20:21], v[20:21], v[24:25]
	v_pk_mul_f32 v[30:31], v[30:31], v[248:249] op_sel_hi:[1,0]
	v_pk_mul_f32 v[32:33], v[32:33], v[248:249] op_sel_hi:[1,0]
	v_pk_mul_f32 v[22:23], v[22:23], v[248:249] op_sel_hi:[1,0]
	v_pk_mul_f32 v[24:25], v[24:25], v[248:249] op_sel_hi:[1,0]
	v_exp_f32_e32 v30, v30
	v_exp_f32_e32 v31, v31
	v_exp_f32_e32 v32, v32
	v_exp_f32_e32 v33, v33
	v_exp_f32_e32 v22, v22
	v_exp_f32_e32 v23, v23
	v_exp_f32_e32 v24, v24
	v_exp_f32_e32 v25, v25
	v_pk_mul_f32 v[26:27], v[26:27], v[250:251] op_sel_hi:[1,0]
	v_pk_mul_f32 v[28:29], v[28:29], v[250:251] op_sel_hi:[1,0]
	v_pk_mul_f32 v[18:19], v[18:19], v[250:251] op_sel_hi:[1,0]
	v_pk_mul_f32 v[20:21], v[20:21], v[250:251] op_sel_hi:[1,0]
	v_pk_add_f32 v[30:31], v[30:31], v[150:151] op_sel_hi:[1,0]
	v_pk_add_f32 v[32:33], v[32:33], v[150:151] op_sel_hi:[1,0]
	v_pk_add_f32 v[22:23], v[22:23], v[150:151] op_sel_hi:[1,0]
	v_pk_add_f32 v[24:25], v[24:25], v[150:151] op_sel_hi:[1,0]
	v_rcp_f32_e32 v30, v30
	v_rcp_f32_e32 v31, v31
	v_rcp_f32_e32 v32, v32
	v_rcp_f32_e32 v33, v33
	v_rcp_f32_e32 v22, v22
	v_rcp_f32_e32 v23, v23
	v_rcp_f32_e32 v24, v24
	v_rcp_f32_e32 v25, v25
	v_pk_mul_f32 v[26:27], v[26:27], v[30:31]
	v_pk_mul_f32 v[28:29], v[28:29], v[32:33]
	v_pk_mul_f32 v[18:19], v[18:19], v[22:23]
	v_pk_mul_f32 v[20:21], v[20:21], v[24:25]
	v_cvt_pk_bf16_f32 v232, v26, v27
	v_cvt_pk_bf16_f32 v233, v28, v29
	v_cvt_pk_bf16_f32 v234, v18, v19
	v_cvt_pk_bf16_f32 v235, v20, v21
	global_store_dwordx4 v[252:253], v[232:235], off
	v_add_co_u32_e32 v252, vcc, 0x16000, v252
	s_nop 1
	v_addc_co_u32_e32 v253, vcc, 0, v253, vcc
	v_mul_f32_e32 v248, 0xbfb8aa3b, v247
	v_mul_f32_e32 v250, v247, v247
	v_pk_mul_f32 v[10:11], v[10:11], v[14:15]
	v_pk_mul_f32 v[12:13], v[12:13], v[16:17]
	v_pk_mul_f32 v[2:3], v[2:3], v[6:7]
	v_pk_mul_f32 v[4:5], v[4:5], v[8:9]
	v_pk_mul_f32 v[14:15], v[14:15], v[248:249] op_sel_hi:[1,0]
	v_pk_mul_f32 v[16:17], v[16:17], v[248:249] op_sel_hi:[1,0]
	v_pk_mul_f32 v[6:7], v[6:7], v[248:249] op_sel_hi:[1,0]
	v_pk_mul_f32 v[8:9], v[8:9], v[248:249] op_sel_hi:[1,0]
	v_exp_f32_e32 v14, v14
	v_exp_f32_e32 v15, v15
	v_exp_f32_e32 v16, v16
	v_exp_f32_e32 v17, v17
	v_exp_f32_e32 v6, v6
	v_exp_f32_e32 v7, v7
	v_exp_f32_e32 v8, v8
	v_exp_f32_e32 v9, v9
	v_pk_mul_f32 v[10:11], v[10:11], v[250:251] op_sel_hi:[1,0]
	v_pk_mul_f32 v[12:13], v[12:13], v[250:251] op_sel_hi:[1,0]
	v_pk_mul_f32 v[2:3], v[2:3], v[250:251] op_sel_hi:[1,0]
	v_pk_mul_f32 v[4:5], v[4:5], v[250:251] op_sel_hi:[1,0]
	v_pk_add_f32 v[14:15], v[14:15], v[150:151] op_sel_hi:[1,0]
	v_pk_add_f32 v[16:17], v[16:17], v[150:151] op_sel_hi:[1,0]
	v_pk_add_f32 v[6:7], v[6:7], v[150:151] op_sel_hi:[1,0]
	v_pk_add_f32 v[8:9], v[8:9], v[150:151] op_sel_hi:[1,0]
	v_rcp_f32_e32 v14, v14
	v_rcp_f32_e32 v15, v15
	v_rcp_f32_e32 v16, v16
	v_rcp_f32_e32 v17, v17
	v_rcp_f32_e32 v6, v6
	v_rcp_f32_e32 v7, v7
	v_rcp_f32_e32 v8, v8
	v_rcp_f32_e32 v9, v9
	v_pk_mul_f32 v[10:11], v[10:11], v[14:15]
	v_pk_mul_f32 v[12:13], v[12:13], v[16:17]
	v_pk_mul_f32 v[2:3], v[2:3], v[6:7]
	v_pk_mul_f32 v[4:5], v[4:5], v[8:9]
	v_cvt_pk_bf16_f32 v236, v10, v11
	v_cvt_pk_bf16_f32 v237, v12, v13
	v_cvt_pk_bf16_f32 v238, v2, v3
	v_cvt_pk_bf16_f32 v239, v4, v5
	global_store_dwordx4 v[252:253], v[236:239], off
	s_mov_b64 s[6:7], -1
	s_andn2_b64 vcc, exec, s[12:13]
	s_cbranch_vccnz .LBB0_300
	s_andn2_b64 vcc, exec, s[2:3]
	s_cbranch_vccnz .LBB0_299
	s_barrier
	s_branch .LBB0_299

; #define LAS __attribute__((address_space(3)))
; __device__ __forceinline__ unsigned cvt_pk_bf16(float lo, float hi) { f32x2_t v = {lo, hi}; bf16x2_t b = __builtin_convertvector(v, bf16x2_t); return __builtin_bit_cast(unsigned, b); }
; __device__ __forceinline__ float sigm(float x) { return __builtin_amdgcn_rcpf(1.0f + __expf(-x)); }
; __device__ __forceinline__ int opaque_tid() { int t = threadIdx.x; asm volatile("" : "+v"(t)); return t; }
;     __device__ __forceinline__ void operator()(AccRef acc, const pg8::Unit& u, int, int, int, int) const {
;         const int tid = opaque_tid(), wid = __builtin_amdgcn_readfirstlane(tid >> 6), wr = wid >> 2, wc = wid & 3, fr = tid & 15, fq = (tid & 63) >> 4;
;         const int row0 = u.pm * 256 + wr * 64 + fr, col0 = u.pn * 128 + wc * 32 + 8 * fq;
; #pragma unroll
;         for (int ai = 0; ai < 2; ++ai)
; #pragma unroll
;             for (int m = 0; m < 4; ++m) {
;                 const int row = row0 + ai * 128 + m * 16; const float rs = ((const LAS float*)((LAS unsigned char*)g_lds + pg8::RSL_OFF))[wid * 128 + ai * 64 + m * 16 + fr];
;                 float o[8];
; #pragma unroll
;                 for (int n = 0; n < 2; ++n)
; #pragma unroll
;                     for (int j = 0; j < 4; ++j) { const float gv = acc[ai][0][m][n][j] * rs, uv = acc[ai][1][m][n][j] * rs; o[n * 4 + j] = gv * sigm(gv) * uv; }
;                 v4u w; w.x = cvt_pk_bf16(o[0], o[1]); w.y = cvt_pk_bf16(o[2], o[3]); w.z = cvt_pk_bf16(o[4], o[5]); w.w = cvt_pk_bf16(o[6], o[7]);
;                 *(v4u*)(O + (size_t)row * DFFP + col0) = w; }
.LBB0_854:
	v_mov_b32_e32 v140, v155
	s_lshl_b32 s11, s30, 7
	v_readfirstlane_b32 s6, v140
	v_and_b32_e32 v141, 15, v140
	s_ashr_i32 s7, s6, 6
	v_or_b32_e32 v142, s1, v141
	s_lshl_b32 s1, s7, 9
	s_ashr_i32 s6, s6, 2
	v_lshl_add_u32 v141, v141, 2, s1
	s_andn2_b32 s6, s6, 63
	v_add_u32_e32 v149, 0x20000, v141
	v_add_u32_e32 v148, s6, v142
	ds_read2_b32 v[240:241], v149 offset1:16
	ds_read2_b32 v[242:243], v149 offset0:32 offset1:48
	ds_read2_b32 v[244:245], v149 offset0:64 offset1:80
	ds_read2_b32 v[246:247], v149 offset0:96 offset1:112
	s_lshl_b32 s18, s7, 5
	v_readlane_b32 s6, v254, 43
	s_and_b32 s18, s18, 0x60
	v_readlane_b32 s7, v254, 44
	s_or_b32 s11, s18, s11
	v_lshrrev_b32_e32 v140, 1, v140
	s_movk_i32 s1, 0x1600
	v_and_or_b32 v140, v140, 24, s11
	v_mov_b32_e32 v150, 1.0
	v_ashrrev_i32_e32 v141, 31, v140
	v_mov_b64_e32 v[142:143], s[6:7]
	v_lshlrev_b64 v[140:141], 1, v[140:141]
	v_mad_i64_i32 v[252:253], s[6:7], v148, s1, v[142:143]
	v_lshl_add_u64 v[252:253], v[252:253], 0, v[140:141]
	s_waitcnt lgkmcnt(0)
	v_mul_f32_e32 v248, 0xbfb8aa3b, v240
	v_mul_f32_e32 v250, v240, v240
	v_pk_mul_f32 v[122:123], v[122:123], v[126:127]
	v_pk_mul_f32 v[124:125], v[124:125], v[128:129]
	v_pk_mul_f32 v[114:115], v[114:115], v[118:119]
	v_pk_mul_f32 v[116:117], v[116:117], v[120:121]
	v_pk_mul_f32 v[126:127], v[126:127], v[248:249] op_sel_hi:[1,0]
	v_pk_mul_f32 v[128:129], v[128:129], v[248:249] op_sel_hi:[1,0]
	v_pk_mul_f32 v[118:119], v[118:119], v[248:249] op_sel_hi:[1,0]
	v_pk_mul_f32 v[120:121], v[120:121], v[248:249] op_sel_hi:[1,0]
	v_exp_f32_e32 v126, v126
	v_exp_f32_e32 v127, v127
	v_exp_f32_e32 v128, v128
	v_exp_f32_e32 v129, v129
	v_exp_f32_e32 v118, v118
	v_exp_f32_e32 v119, v119
	v_exp_f32_e32 v120, v120
	v_exp_f32_e32 v121, v121
	v_pk_mul_f32 v[122:123], v[122:123], v[250:251] op_sel_hi:[1,0]
	v_pk_mul_f32 v[124:125], v[124:125], v[250:251] op_sel_hi:[1,0]
	v_pk_mul_f32 v[114:115], v[114:115], v[250:251] op_sel_hi:[1,0]
	v_pk_mul_f32 v[116:117], v[116:117], v[250:251] op_sel_hi:[1,0]
	v_pk_add_f32 v[126:127], v[126:127], v[150:151] op_sel_hi:[1,0]
	v_pk_add_f32 v[128:129], v[128:129], v[150:151] op_sel_hi:[1,0]
	v_pk_add_f32 v[118:119], v[118:119], v[150:151] op_sel_hi:[1,0]
	v_pk_add_f32 v[120:121], v[120:121], v[150:151] op_sel_hi:[1,0]
	v_rcp_f32_e32 v126, v126
	v_rcp_f32_e32 v127, v127
	v_rcp_f32_e32 v128, v128
	v_rcp_f32_e32 v129, v129
	v_rcp_f32_e32 v118, v118
	v_rcp_f32_e32 v119, v119
	v_rcp_f32_e32 v120, v120
	v_rcp_f32_e32 v121, v121
	v_pk_mul_f32 v[122:123], v[122:123], v[126:127]
	v_pk_mul_f32 v[124:125], v[124:125], v[128:129]
	v_pk_mul_f32 v[114:115], v[114:115], v[118:119]
	v_pk_mul_f32 v[116:117], v[116:117], v[120:121]
	v_cvt_pk_bf16_f32 v232, v122, v123
	v_cvt_pk_bf16_f32 v233, v124, v125
	v_cvt_pk_bf16_f32 v234, v114, v115
	v_cvt_pk_bf16_f32 v235, v116, v117
	global_store_dwordx4 v[252:253], v[232:235], off
	v_add_co_u32_e32 v252, vcc, 0x16000, v252
	s_nop 1
	v_addc_co_u32_e32 v253, vcc, 0, v253, vcc
	v_mul_f32_e32 v248, 0xbfb8aa3b, v241
	v_mul_f32_e32 v250, v241, v241
	v_pk_mul_f32 v[106:107], v[106:107], v[110:111]
	v_pk_mul_f32 v[108:109], v[108:109], v[112:113]
	v_pk_mul_f32 v[98:99], v[98:99], v[102:103]
	v_pk_mul_f32 v[100:101], v[100:101], v[104:105]
	v_pk_mul_f32 v[110:111], v[110:111], v[248:249] op_sel_hi:[1,0]
	v_pk_mul_f32 v[112:113], v[112:113], v[248:249] op_sel_hi:[1,0]
	v_pk_mul_f32 v[102:103], v[102:103], v[248:249] op_sel_hi:[1,0]
	v_pk_mul_f32 v[104:105], v[104:105], v[248:249] op_sel_hi:[1,0]
	v_exp_f32_e32 v110, v110
	v_exp_f32_e32 v111, v111
	v_exp_f32_e32 v112, v112
	v_exp_f32_e32 v113, v113
	v_exp_f32_e32 v102, v102
	v_exp_f32_e32 v103, v103
	v_exp_f32_e32 v104, v104
	v_exp_f32_e32 v105, v105
	v_pk_mul_f32 v[106:107], v[106:107], v[250:251] op_sel_hi:[1,0]
	v_pk_mul_f32 v[108:109], v[108:109], v[250:251] op_sel_hi:[1,0]
	v_pk_mul_f32 v[98:99], v[98:99], v[250:251] op_sel_hi:[1,0]
	v_pk_mul_f32 v[100:101], v[100:101], v[250:251] op_sel_hi:[1,0]
	v_pk_add_f32 v[110:111], v[110:111], v[150:151] op_sel_hi:[1,0]
	v_pk_add_f32 v[112:113], v[112:113], v[150:151] op_sel_hi:[1,0]
	v_pk_add_f32 v[102:103], v[102:103], v[150:151] op_sel_hi:[1,0]
	v_pk_add_f32 v[104:105], v[104:105], v[150:151] op_sel_hi:[1,0]
	v_rcp_f32_e32 v110, v110
	v_rcp_f32_e32 v111, v111
	v_rcp_f32_e32 v112, v112
	v_rcp_f32_e32 v113, v113
	v_rcp_f32_e32 v102, v102
	v_rcp_f32_e32 v103, v103
	v_rcp_f32_e32 v104, v104
	v_rcp_f32_e32 v105, v105
	v_pk_mul_f32 v[106:107], v[106:107], v[110:111]
	v_pk_mul_f32 v[108:109], v[108:109], v[112:113]
	v_pk_mul_f32 v[98:99], v[98:99], v[102:103]
	v_pk_mul_f32 v[100:101], v[100:101], v[104:105]
	v_cvt_pk_bf16_f32 v236, v106, v107
	v_cvt_pk_bf16_f32 v237, v108, v109
	v_cvt_pk_bf16_f32 v238, v98, v99
	v_cvt_pk_bf16_f32 v239, v100, v101
	global_store_dwordx4 v[252:253], v[236:239], off
	v_add_co_u32_e32 v252, vcc, 0x16000, v252
	s_nop 1
	v_addc_co_u32_e32 v253, vcc, 0, v253, vcc
	v_mul_f32_e32 v248, 0xbfb8aa3b, v242
	v_mul_f32_e32 v250, v242, v242
	v_pk_mul_f32 v[90:91], v[90:91], v[94:95]
	v_pk_mul_f32 v[92:93], v[92:93], v[96:97]
	v_pk_mul_f32 v[82:83], v[82:83], v[86:87]
	v_pk_mul_f32 v[84:85], v[84:85], v[88:89]
	v_pk_mul_f32 v[94:95], v[94:95], v[248:249] op_sel_hi:[1,0]
	v_pk_mul_f32 v[96:97], v[96:97], v[248:249] op_sel_hi:[1,0]
	v_pk_mul_f32 v[86:87], v[86:87], v[248:249] op_sel_hi:[1,0]
	v_pk_mul_f32 v[88:89], v[88:89], v[248:249] op_sel_hi:[1,0]
	v_exp_f32_e32 v94, v94
	v_exp_f32_e32 v95, v95
	v_exp_f32_e32 v96, v96
	v_exp_f32_e32 v97, v97
	v_exp_f32_e32 v86, v86
	v_exp_f32_e32 v87, v87
	v_exp_f32_e32 v88, v88
	v_exp_f32_e32 v89, v89
	v_pk_mul_f32 v[90:91], v[90:91], v[250:251] op_sel_hi:[1,0]
; #define LAS __attribute__((address_space(3)))
; __device__ __forceinline__ unsigned cvt_pk_bf16(float lo, float hi) { f32x2_t v = {lo, hi}; bf16x2_t b = __builtin_convertvector(v, bf16x2_t); return __builtin_bit_cast(unsigned, b); }
; __device__ __forceinline__ float sigm(float x) { return __builtin_amdgcn_rcpf(1.0f + __expf(-x)); }
;     __device__ __forceinline__ void operator()(AccRef acc, const pg8::Unit& u, int, int, int, int) const {
;     ...
;                 const int row = row0 + ai * 128 + m * 16; const float rs = ((const LAS float*)((LAS unsigned char*)g_lds + pg8::RSL_OFF))[wid * 128 + ai * 64 + m * 16 + fr];
;                 float o[8];
; #pragma unroll
;                 for (int n = 0; n < 2; ++n)
; #pragma unroll
;                     for (int j = 0; j < 4; ++j) { const float gv = acc[ai][0][m][n][j] * rs, uv = acc[ai][1][m][n][j] * rs; o[n * 4 + j] = gv * sigm(gv) * uv; }
;                 v4u w; w.x = cvt_pk_bf16(o[0], o[1]); w.y = cvt_pk_bf16(o[2], o[3]); w.z = cvt_pk_bf16(o[4], o[5]); w.w = cvt_pk_bf16(o[6], o[7]);
;                 *(v4u*)(O + (size_t)row * DFFP + col0) = w; }
	v_pk_mul_f32 v[92:93], v[92:93], v[250:251] op_sel_hi:[1,0]
	v_pk_mul_f32 v[82:83], v[82:83], v[250:251] op_sel_hi:[1,0]
	v_pk_mul_f32 v[84:85], v[84:85], v[250:251] op_sel_hi:[1,0]
	v_pk_add_f32 v[94:95], v[94:95], v[150:151] op_sel_hi:[1,0]
	v_pk_add_f32 v[96:97], v[96:97], v[150:151] op_sel_hi:[1,0]
	v_pk_add_f32 v[86:87], v[86:87], v[150:151] op_sel_hi:[1,0]
	v_pk_add_f32 v[88:89], v[88:89], v[150:151] op_sel_hi:[1,0]
	v_rcp_f32_e32 v94, v94
	v_rcp_f32_e32 v95, v95
	v_rcp_f32_e32 v96, v96
	v_rcp_f32_e32 v97, v97
	v_rcp_f32_e32 v86, v86
	v_rcp_f32_e32 v87, v87
	v_rcp_f32_e32 v88, v88
	v_rcp_f32_e32 v89, v89
	v_pk_mul_f32 v[90:91], v[90:91], v[94:95]
	v_pk_mul_f32 v[92:93], v[92:93], v[96:97]
	v_pk_mul_f32 v[82:83], v[82:83], v[86:87]
	v_pk_mul_f32 v[84:85], v[84:85], v[88:89]
	v_cvt_pk_bf16_f32 v232, v90, v91
	v_cvt_pk_bf16_f32 v233, v92, v93
	v_cvt_pk_bf16_f32 v234, v82, v83
	v_cvt_pk_bf16_f32 v235, v84, v85
	global_store_dwordx4 v[252:253], v[232:235], off
	v_add_co_u32_e32 v252, vcc, 0x16000, v252
	s_nop 1
	v_addc_co_u32_e32 v253, vcc, 0, v253, vcc
	v_mul_f32_e32 v248, 0xbfb8aa3b, v243
	v_mul_f32_e32 v250, v243, v243
	v_pk_mul_f32 v[74:75], v[74:75], v[78:79]
	v_pk_mul_f32 v[76:77], v[76:77], v[80:81]
	v_pk_mul_f32 v[66:67], v[66:67], v[70:71]
	v_pk_mul_f32 v[68:69], v[68:69], v[72:73]
	v_pk_mul_f32 v[78:79], v[78:79], v[248:249] op_sel_hi:[1,0]
	v_pk_mul_f32 v[80:81], v[80:81], v[248:249] op_sel_hi:[1,0]
	v_pk_mul_f32 v[70:71], v[70:71], v[248:249] op_sel_hi:[1,0]
	v_pk_mul_f32 v[72:73], v[72:73], v[248:249] op_sel_hi:[1,0]
	v_exp_f32_e32 v78, v78
	v_exp_f32_e32 v79, v79
	v_exp_f32_e32 v80, v80
	v_exp_f32_e32 v81, v81
	v_exp_f32_e32 v70, v70
	v_exp_f32_e32 v71, v71
	v_exp_f32_e32 v72, v72
	v_exp_f32_e32 v73, v73
	v_pk_mul_f32 v[74:75], v[74:75], v[250:251] op_sel_hi:[1,0]
	v_pk_mul_f32 v[76:77], v[76:77], v[250:251] op_sel_hi:[1,0]
	v_pk_mul_f32 v[66:67], v[66:67], v[250:251] op_sel_hi:[1,0]
	v_pk_mul_f32 v[68:69], v[68:69], v[250:251] op_sel_hi:[1,0]
	v_pk_add_f32 v[78:79], v[78:79], v[150:151] op_sel_hi:[1,0]
	v_pk_add_f32 v[80:81], v[80:81], v[150:151] op_sel_hi:[1,0]
	v_pk_add_f32 v[70:71], v[70:71], v[150:151] op_sel_hi:[1,0]
	v_pk_add_f32 v[72:73], v[72:73], v[150:151] op_sel_hi:[1,0]
	v_rcp_f32_e32 v78, v78
	v_rcp_f32_e32 v79, v79
	v_rcp_f32_e32 v80, v80
	v_rcp_f32_e32 v81, v81
	v_rcp_f32_e32 v70, v70
	v_rcp_f32_e32 v71, v71
	v_rcp_f32_e32 v72, v72
	v_rcp_f32_e32 v73, v73
	v_pk_mul_f32 v[74:75], v[74:75], v[78:79]
	v_pk_mul_f32 v[76:77], v[76:77], v[80:81]
	v_pk_mul_f32 v[66:67], v[66:67], v[70:71]
	v_pk_mul_f32 v[68:69], v[68:69], v[72:73]
	v_cvt_pk_bf16_f32 v236, v74, v75
	v_cvt_pk_bf16_f32 v237, v76, v77
	v_cvt_pk_bf16_f32 v238, v66, v67
	v_cvt_pk_bf16_f32 v239, v68, v69
	global_store_dwordx4 v[252:253], v[236:239], off
	v_add_co_u32_e32 v252, vcc, 0x6e000, v252
	s_nop 1
	v_addc_co_u32_e32 v253, vcc, 0, v253, vcc
	v_mul_f32_e32 v248, 0xbfb8aa3b, v244
	v_mul_f32_e32 v250, v244, v244
	v_pk_mul_f32 v[58:59], v[58:59], v[62:63]
	v_pk_mul_f32 v[60:61], v[60:61], v[64:65]
	v_pk_mul_f32 v[50:51], v[50:51], v[54:55]
	v_pk_mul_f32 v[52:53], v[52:53], v[56:57]
	v_pk_mul_f32 v[62:63], v[62:63], v[248:249] op_sel_hi:[1,0]
	v_pk_mul_f32 v[64:65], v[64:65], v[248:249] op_sel_hi:[1,0]
	v_pk_mul_f32 v[54:55], v[54:55], v[248:249] op_sel_hi:[1,0]
	v_pk_mul_f32 v[56:57], v[56:57], v[248:249] op_sel_hi:[1,0]
	v_exp_f32_e32 v62, v62
	v_exp_f32_e32 v63, v63
	v_exp_f32_e32 v64, v64
	v_exp_f32_e32 v65, v65
	v_exp_f32_e32 v54, v54
	v_exp_f32_e32 v55, v55
	v_exp_f32_e32 v56, v56
	v_exp_f32_e32 v57, v57
	v_pk_mul_f32 v[58:59], v[58:59], v[250:251] op_sel_hi:[1,0]
	v_pk_mul_f32 v[60:61], v[60:61], v[250:251] op_sel_hi:[1,0]
	v_pk_mul_f32 v[50:51], v[50:51], v[250:251] op_sel_hi:[1,0]
	v_pk_mul_f32 v[52:53], v[52:53], v[250:251] op_sel_hi:[1,0]
	v_pk_add_f32 v[62:63], v[62:63], v[150:151] op_sel_hi:[1,0]
	v_pk_add_f32 v[64:65], v[64:65], v[150:151] op_sel_hi:[1,0]
	v_pk_add_f32 v[54:55], v[54:55], v[150:151] op_sel_hi:[1,0]
	v_pk_add_f32 v[56:57], v[56:57], v[150:151] op_sel_hi:[1,0]
	v_rcp_f32_e32 v62, v62
	v_rcp_f32_e32 v63, v63
	v_rcp_f32_e32 v64, v64
	v_rcp_f32_e32 v65, v65
	v_rcp_f32_e32 v54, v54
	v_rcp_f32_e32 v55, v55
	v_rcp_f32_e32 v56, v56
	v_rcp_f32_e32 v57, v57
	v_pk_mul_f32 v[58:59], v[58:59], v[62:63]
	v_pk_mul_f32 v[60:61], v[60:61], v[64:65]
	v_pk_mul_f32 v[50:51], v[50:51], v[54:55]
	v_pk_mul_f32 v[52:53], v[52:53], v[56:57]
	v_cvt_pk_bf16_f32 v232, v58, v59
	v_cvt_pk_bf16_f32 v233, v60, v61
	v_cvt_pk_bf16_f32 v234, v50, v51
	v_cvt_pk_bf16_f32 v235, v52, v53
	global_store_dwordx4 v[252:253], v[232:235], off
	v_add_co_u32_e32 v252, vcc, 0x16000, v252
	s_nop 1
	v_addc_co_u32_e32 v253, vcc, 0, v253, vcc
	v_mul_f32_e32 v248, 0xbfb8aa3b, v245
	v_mul_f32_e32 v250, v245, v245
	v_pk_mul_f32 v[42:43], v[42:43], v[46:47]
	v_pk_mul_f32 v[44:45], v[44:45], v[48:49]
	v_pk_mul_f32 v[34:35], v[34:35], v[38:39]
	v_pk_mul_f32 v[36:37], v[36:37], v[40:41]
	v_pk_mul_f32 v[46:47], v[46:47], v[248:249] op_sel_hi:[1,0]
	v_pk_mul_f32 v[48:49], v[48:49], v[248:249] op_sel_hi:[1,0]
; #define LAS __attribute__((address_space(3)))
; __device__ __forceinline__ unsigned cvt_pk_bf16(float lo, float hi) { f32x2_t v = {lo, hi}; bf16x2_t b = __builtin_convertvector(v, bf16x2_t); return __builtin_bit_cast(unsigned, b); }
; __device__ __forceinline__ float sigm(float x) { return __builtin_amdgcn_rcpf(1.0f + __expf(-x)); }
; #define PG8_BAR __builtin_amdgcn_s_barrier()
; template <class Epi, bool ALIGN_EPI>
; __device__ __forceinline__ void gemm_phase(LAS unsigned char* lds, const Gemm g, const StaticOrder& S, const Epi& E) {
;     ...
;         if (!has_next) break;
; #pragma unroll
;         for (int a = 0; a < 2; ++a)
; #pragma unroll
;             for (int b = 0; b < 2; ++b)
; #pragma unroll
;                 for (int m = 0; m < 4; ++m)
; #pragma unroll
;                     for (int n = 0; n < 2; ++n) acc[a][b][m][n] = (f32x4){0.f, 0.f, 0.f, 0.f};
;         cur = nxt; cA = nA; cB = nB; ++ui;
;         if constexpr (ALIGN_EPI) { if (wr == 1) PG8_BAR; }
;     __device__ __forceinline__ void operator()(AccRef acc, const pg8::Unit& u, int, int, int, int) const {
;     ...
;                 const int row = row0 + ai * 128 + m * 16; const float rs = ((const LAS float*)((LAS unsigned char*)g_lds + pg8::RSL_OFF))[wid * 128 + ai * 64 + m * 16 + fr];
;                 float o[8];
; #pragma unroll
;                 for (int n = 0; n < 2; ++n)
; #pragma unroll
;                     for (int j = 0; j < 4; ++j) { const float gv = acc[ai][0][m][n][j] * rs, uv = acc[ai][1][m][n][j] * rs; o[n * 4 + j] = gv * sigm(gv) * uv; }
;                 v4u w; w.x = cvt_pk_bf16(o[0], o[1]); w.y = cvt_pk_bf16(o[2], o[3]); w.z = cvt_pk_bf16(o[4], o[5]); w.w = cvt_pk_bf16(o[6], o[7]);
;                 *(v4u*)(O + (size_t)row * DFFP + col0) = w; }
	v_pk_mul_f32 v[38:39], v[38:39], v[248:249] op_sel_hi:[1,0]
	v_pk_mul_f32 v[40:41], v[40:41], v[248:249] op_sel_hi:[1,0]
	v_exp_f32_e32 v46, v46
	v_exp_f32_e32 v47, v47
	v_exp_f32_e32 v48, v48
	v_exp_f32_e32 v49, v49
	v_exp_f32_e32 v38, v38
	v_exp_f32_e32 v39, v39
	v_exp_f32_e32 v40, v40
	v_exp_f32_e32 v41, v41
	v_pk_mul_f32 v[42:43], v[42:43], v[250:251] op_sel_hi:[1,0]
	v_pk_mul_f32 v[44:45], v[44:45], v[250:251] op_sel_hi:[1,0]
	v_pk_mul_f32 v[34:35], v[34:35], v[250:251] op_sel_hi:[1,0]
	v_pk_mul_f32 v[36:37], v[36:37], v[250:251] op_sel_hi:[1,0]
	v_pk_add_f32 v[46:47], v[46:47], v[150:151] op_sel_hi:[1,0]
	v_pk_add_f32 v[48:49], v[48:49], v[150:151] op_sel_hi:[1,0]
	v_pk_add_f32 v[38:39], v[38:39], v[150:151] op_sel_hi:[1,0]
	v_pk_add_f32 v[40:41], v[40:41], v[150:151] op_sel_hi:[1,0]
	v_rcp_f32_e32 v46, v46
	v_rcp_f32_e32 v47, v47
	v_rcp_f32_e32 v48, v48
	v_rcp_f32_e32 v49, v49
	v_rcp_f32_e32 v38, v38
	v_rcp_f32_e32 v39, v39
	v_rcp_f32_e32 v40, v40
	v_rcp_f32_e32 v41, v41
	v_pk_mul_f32 v[42:43], v[42:43], v[46:47]
	v_pk_mul_f32 v[44:45], v[44:45], v[48:49]
	v_pk_mul_f32 v[34:35], v[34:35], v[38:39]
	v_pk_mul_f32 v[36:37], v[36:37], v[40:41]
	v_cvt_pk_bf16_f32 v236, v42, v43
	v_cvt_pk_bf16_f32 v237, v44, v45
	v_cvt_pk_bf16_f32 v238, v34, v35
	v_cvt_pk_bf16_f32 v239, v36, v37
	global_store_dwordx4 v[252:253], v[236:239], off
	v_add_co_u32_e32 v252, vcc, 0x16000, v252
	s_nop 1
	v_addc_co_u32_e32 v253, vcc, 0, v253, vcc
	v_mul_f32_e32 v248, 0xbfb8aa3b, v246
	v_mul_f32_e32 v250, v246, v246
	v_pk_mul_f32 v[26:27], v[26:27], v[30:31]
	v_pk_mul_f32 v[28:29], v[28:29], v[32:33]
	v_pk_mul_f32 v[18:19], v[18:19], v[22:23]
	v_pk_mul_f32 v[20:21], v[20:21], v[24:25]
	v_pk_mul_f32 v[30:31], v[30:31], v[248:249] op_sel_hi:[1,0]
	v_pk_mul_f32 v[32:33], v[32:33], v[248:249] op_sel_hi:[1,0]
	v_pk_mul_f32 v[22:23], v[22:23], v[248:249] op_sel_hi:[1,0]
	v_pk_mul_f32 v[24:25], v[24:25], v[248:249] op_sel_hi:[1,0]
	v_exp_f32_e32 v30, v30
	v_exp_f32_e32 v31, v31
	v_exp_f32_e32 v32, v32
	v_exp_f32_e32 v33, v33
	v_exp_f32_e32 v22, v22
	v_exp_f32_e32 v23, v23
	v_exp_f32_e32 v24, v24
	v_exp_f32_e32 v25, v25
	v_pk_mul_f32 v[26:27], v[26:27], v[250:251] op_sel_hi:[1,0]
	v_pk_mul_f32 v[28:29], v[28:29], v[250:251] op_sel_hi:[1,0]
	v_pk_mul_f32 v[18:19], v[18:19], v[250:251] op_sel_hi:[1,0]
	v_pk_mul_f32 v[20:21], v[20:21], v[250:251] op_sel_hi:[1,0]
	v_pk_add_f32 v[30:31], v[30:31], v[150:151] op_sel_hi:[1,0]
	v_pk_add_f32 v[32:33], v[32:33], v[150:151] op_sel_hi:[1,0]
	v_pk_add_f32 v[22:23], v[22:23], v[150:151] op_sel_hi:[1,0]
	v_pk_add_f32 v[24:25], v[24:25], v[150:151] op_sel_hi:[1,0]
	v_rcp_f32_e32 v30, v30
	v_rcp_f32_e32 v31, v31
	v_rcp_f32_e32 v32, v32
	v_rcp_f32_e32 v33, v33
	v_rcp_f32_e32 v22, v22
	v_rcp_f32_e32 v23, v23
	v_rcp_f32_e32 v24, v24
	v_rcp_f32_e32 v25, v25
	v_pk_mul_f32 v[26:27], v[26:27], v[30:31]
	v_pk_mul_f32 v[28:29], v[28:29], v[32:33]
	v_pk_mul_f32 v[18:19], v[18:19], v[22:23]
	v_pk_mul_f32 v[20:21], v[20:21], v[24:25]
	v_cvt_pk_bf16_f32 v232, v26, v27
	v_cvt_pk_bf16_f32 v233, v28, v29
	v_cvt_pk_bf16_f32 v234, v18, v19
	v_cvt_pk_bf16_f32 v235, v20, v21
	global_store_dwordx4 v[252:253], v[232:235], off
	v_add_co_u32_e32 v252, vcc, 0x16000, v252
	s_nop 1
	v_addc_co_u32_e32 v253, vcc, 0, v253, vcc
	v_mul_f32_e32 v248, 0xbfb8aa3b, v247
	v_mul_f32_e32 v250, v247, v247
	v_pk_mul_f32 v[10:11], v[10:11], v[14:15]
	v_pk_mul_f32 v[12:13], v[12:13], v[16:17]
	v_pk_mul_f32 v[2:3], v[2:3], v[6:7]
	v_pk_mul_f32 v[4:5], v[4:5], v[8:9]
	v_pk_mul_f32 v[14:15], v[14:15], v[248:249] op_sel_hi:[1,0]
	v_pk_mul_f32 v[16:17], v[16:17], v[248:249] op_sel_hi:[1,0]
	v_pk_mul_f32 v[6:7], v[6:7], v[248:249] op_sel_hi:[1,0]
	v_pk_mul_f32 v[8:9], v[8:9], v[248:249] op_sel_hi:[1,0]
	v_exp_f32_e32 v14, v14
	v_exp_f32_e32 v15, v15
	v_exp_f32_e32 v16, v16
	v_exp_f32_e32 v17, v17
	v_exp_f32_e32 v6, v6
	v_exp_f32_e32 v7, v7
	v_exp_f32_e32 v8, v8
	v_exp_f32_e32 v9, v9
	v_pk_mul_f32 v[10:11], v[10:11], v[250:251] op_sel_hi:[1,0]
	v_pk_mul_f32 v[12:13], v[12:13], v[250:251] op_sel_hi:[1,0]
	v_pk_mul_f32 v[2:3], v[2:3], v[250:251] op_sel_hi:[1,0]
	v_pk_mul_f32 v[4:5], v[4:5], v[250:251] op_sel_hi:[1,0]
	v_pk_add_f32 v[14:15], v[14:15], v[150:151] op_sel_hi:[1,0]
	v_pk_add_f32 v[16:17], v[16:17], v[150:151] op_sel_hi:[1,0]
	v_pk_add_f32 v[6:7], v[6:7], v[150:151] op_sel_hi:[1,0]
	v_pk_add_f32 v[8:9], v[8:9], v[150:151] op_sel_hi:[1,0]
	v_rcp_f32_e32 v14, v14
	v_rcp_f32_e32 v15, v15
	v_rcp_f32_e32 v16, v16
	v_rcp_f32_e32 v17, v17
	v_rcp_f32_e32 v6, v6
	v_rcp_f32_e32 v7, v7
	v_rcp_f32_e32 v8, v8
	v_rcp_f32_e32 v9, v9
	v_pk_mul_f32 v[10:11], v[10:11], v[14:15]
	v_pk_mul_f32 v[12:13], v[12:13], v[16:17]
	v_pk_mul_f32 v[2:3], v[2:3], v[6:7]
	v_pk_mul_f32 v[4:5], v[4:5], v[8:9]
	v_cvt_pk_bf16_f32 v236, v10, v11
	v_cvt_pk_bf16_f32 v237, v12, v13
	v_cvt_pk_bf16_f32 v238, v2, v3
	v_cvt_pk_bf16_f32 v239, v4, v5
	global_store_dwordx4 v[252:253], v[236:239], off
	s_mov_b64 s[6:7], -1
	s_andn2_b64 vcc, exec, s[12:13]
	s_cbranch_vccnz .LBB0_845
	s_andn2_b64 vcc, exec, s[2:3]
	s_cbranch_vccnz .LBB0_844
	s_barrier
	s_branch .LBB0_844
